# attnA epilogue diff_subln gain loads batched (15 loads in flight)
# baseline (speedup 1.0000x reference)
; DI void task_attnA(const P& p, int layer, int task, bf16_t* sm, int dm) {
;     ...
;   if (c == 1) {
; #pragma unroll
;     for (int dt = 0; dt < 4; ++dt)
; #pragma unroll
;       for (int i = 0; i < 16; ++i) {
;         const int d = dt * 32 + 8 * (i >> 2) + 4 * lh + (i & 3);
;         xbuf[(qs * 128 + d) * 32 + lr] = O[dt][i] * inv;
;       }
;   }
;   __syncthreads();
;   if (c == 0) {
;     const float lam = ((const float*)(p.ws + O_LAM))[layer];
;     const float li = 0.8f - 0.6f * expf(-0.3f * (float)layer);
;     float ss = 0.f;
; #pragma unroll
;     for (int dt = 0; dt < 4; ++dt)
; #pragma unroll
;       for (int i = 0; i < 16; ++i) {
;         const int d = dt * 32 + 8 * (i >> 2) + 4 * lh + (i & 3);
;         const float o = O[dt][i] * inv - lam * xbuf[(qs * 128 + d) * 32 + lr];
;         O[dt][i] = o;
;         ss += o * o;
;       }
.LBB0_1054:
	s_or_b64 exec, exec, s[2:3]
	s_waitcnt lgkmcnt(0)
	s_barrier
	s_and_saveexec_b64 s[0:1], vcc
	s_xor_b64 s[0:1], exec, s[0:1]
	s_cbranch_execz .LBB0_1056
	v_readlane_b32 s2, v255, 23
	v_readlane_b32 s3, v255, 24
	v_and_b32_e32 v70, 0x1ffff80, v138
	v_lshlrev_b32_e32 v70, 7, v70
	v_lshlrev_b32_e32 v71, 2, v139
	v_lshl_or_b32 v70, v137, 9, v70
	v_add3_u32 v73, 0, v71, v70
	global_load_dword v72, v193, s[2:3]
	global_load_dwordx4 v[64:67], v192, s[26:27]
	ds_read2_b32 v[70:71], v73 offset1:32
	ds_read2_b32 v[74:75], v73 offset0:64 offset1:96
	v_add_u32_e32 v78, 0x400, v73
	v_add_u32_e32 v82, 0x800, v73
	v_add_u32_e32 v86, 0xc00, v73
	v_add_u32_e32 v90, 0x1000, v73
	v_add_u32_e32 v94, 0x1400, v73
	s_waitcnt vmcnt(5)
	v_add_u32_e32 v98, 0x1800, v73
	s_waitcnt vmcnt(4)
	v_add_u32_e32 v102, 0x1c00, v73
	s_waitcnt vmcnt(3)
	v_add_u32_e32 v106, 0x2000, v73
	s_waitcnt vmcnt(2)
	v_add_u32_e32 v110, 0x2400, v73
	v_add_u32_e32 v114, 0x2800, v73
	v_add_u32_e32 v118, 0x2c00, v73
	v_add_u32_e32 v122, 0x3000, v73
	v_add_u32_e32 v132, 0x3400, v73
	v_add_u32_e32 v138, 0x3800, v73
	v_add_u32_e32 v73, 0x3c00, v73
	ds_read2_b32 v[76:77], v78 offset1:32
	ds_read2_b32 v[78:79], v78 offset0:64 offset1:96
	ds_read2_b32 v[80:81], v82 offset1:32
	ds_read2_b32 v[82:83], v82 offset0:64 offset1:96
	ds_read2_b32 v[84:85], v86 offset1:32
	ds_read2_b32 v[86:87], v86 offset0:64 offset1:96
	ds_read2_b32 v[88:89], v90 offset1:32
	ds_read2_b32 v[90:91], v90 offset0:64 offset1:96
	ds_read2_b32 v[92:93], v94 offset1:32
	ds_read2_b32 v[94:95], v94 offset0:64 offset1:96
	ds_read2_b32 v[96:97], v98 offset1:32
	ds_read2_b32 v[98:99], v98 offset0:64 offset1:96
	ds_read2_b32 v[100:101], v102 offset1:32
	ds_read2_b32 v[102:103], v102 offset0:64 offset1:96
	ds_read2_b32 v[104:105], v106 offset1:32
	ds_read2_b32 v[106:107], v106 offset0:64 offset1:96
	ds_read2_b32 v[108:109], v110 offset1:32
	ds_read2_b32 v[110:111], v110 offset0:64 offset1:96
	ds_read2_b32 v[112:113], v114 offset1:32
	ds_read2_b32 v[114:115], v114 offset0:64 offset1:96
	ds_read2_b32 v[116:117], v118 offset1:32
	ds_read2_b32 v[118:119], v118 offset0:64 offset1:96
	ds_read2_b32 v[120:121], v122 offset1:32
	ds_read2_b32 v[122:123], v122 offset0:64 offset1:96
	ds_read2_b32 v[126:127], v132 offset1:32
	ds_read2_b32 v[128:129], v73 offset1:32
	ds_read2_b32 v[130:131], v73 offset0:64 offset1:96
	ds_read2_b32 v[132:133], v132 offset0:64 offset1:96
	ds_read2_b32 v[134:135], v138 offset1:32
	ds_read2_b32 v[138:139], v138 offset0:64 offset1:96
	s_waitcnt vmcnt(1) lgkmcnt(4)
	v_pk_mul_f32 v[128:129], v[72:73], v[128:129] op_sel_hi:[0,1]
	s_waitcnt lgkmcnt(3)
	v_pk_mul_f32 v[130:131], v[72:73], v[130:131] op_sel_hi:[0,1]
	v_pk_mul_f32 v[74:75], v[72:73], v[74:75] op_sel_hi:[0,1]
	v_pk_mul_f32 v[140:141], v[72:73], v[70:71] op_sel_hi:[0,1]
	v_pk_fma_f32 v[70:71], v[12:13], v[68:69], v[128:129] op_sel_hi:[1,0,1] neg_lo:[0,0,1] neg_hi:[0,0,1]
	v_pk_fma_f32 v[12:13], v[14:15], v[68:69], v[130:131] op_sel_hi:[1,0,1] neg_lo:[0,0,1] neg_hi:[0,0,1]
	v_pk_mul_f32 v[14:15], v[72:73], v[90:91] op_sel_hi:[0,1]
	v_pk_mul_f32 v[78:79], v[72:73], v[78:79] op_sel_hi:[0,1]
	v_pk_fma_f32 v[128:129], v[50:51], v[68:69], v[74:75] op_sel_hi:[1,0,1] neg_lo:[0,0,1] neg_hi:[0,0,1]
	v_pk_fma_f32 v[50:51], v[34:35], v[68:69], v[14:15] op_sel_hi:[1,0,1] neg_lo:[0,0,1] neg_hi:[0,0,1]
	v_pk_mul_f32 v[14:15], v[72:73], v[88:89] op_sel_hi:[0,1]
	v_pk_fma_f32 v[78:79], v[54:55], v[68:69], v[78:79] op_sel_hi:[1,0,1] neg_lo:[0,0,1] neg_hi:[0,0,1]
	v_pk_fma_f32 v[54:55], v[32:33], v[68:69], v[14:15] op_sel_hi:[1,0,1] neg_lo:[0,0,1] neg_hi:[0,0,1]
	v_pk_mul_f32 v[14:15], v[72:73], v[94:95] op_sel_hi:[0,1]
	v_pk_mul_f32 v[76:77], v[72:73], v[76:77] op_sel_hi:[0,1]
	v_pk_mul_f32 v[142:143], v[72:73], v[80:81] op_sel_hi:[0,1]
	v_pk_fma_f32 v[32:33], v[38:39], v[68:69], v[14:15] op_sel_hi:[1,0,1] neg_lo:[0,0,1] neg_hi:[0,0,1]
	v_pk_mul_f32 v[14:15], v[72:73], v[92:93] op_sel_hi:[0,1]
	v_pk_fma_f32 v[80:81], v[52:53], v[68:69], v[76:77] op_sel_hi:[1,0,1] neg_lo:[0,0,1] neg_hi:[0,0,1]
	v_pk_fma_f32 v[76:77], v[56:57], v[68:69], v[142:143] op_sel_hi:[1,0,1] neg_lo:[0,0,1] neg_hi:[0,0,1]
	v_pk_fma_f32 v[56:57], v[36:37], v[68:69], v[14:15] op_sel_hi:[1,0,1] neg_lo:[0,0,1] neg_hi:[0,0,1]
	v_pk_mul_f32 v[14:15], v[72:73], v[98:99] op_sel_hi:[0,1]
	v_pk_mul_f32 v[82:83], v[72:73], v[82:83] op_sel_hi:[0,1]
	v_pk_fma_f32 v[34:35], v[42:43], v[68:69], v[14:15] op_sel_hi:[1,0,1] neg_lo:[0,0,1] neg_hi:[0,0,1]
	v_pk_mul_f32 v[14:15], v[72:73], v[96:97] op_sel_hi:[0,1]
	v_pk_fma_f32 v[74:75], v[58:59], v[68:69], v[82:83] op_sel_hi:[1,0,1] neg_lo:[0,0,1] neg_hi:[0,0,1]
	v_pk_fma_f32 v[58:59], v[40:41], v[68:69], v[14:15] op_sel_hi:[1,0,1] neg_lo:[0,0,1] neg_hi:[0,0,1]
	v_pk_mul_f32 v[14:15], v[72:73], v[102:103] op_sel_hi:[0,1]
	v_pk_fma_f32 v[36:37], v[46:47], v[68:69], v[14:15] op_sel_hi:[1,0,1] neg_lo:[0,0,1] neg_hi:[0,0,1]
	v_pk_mul_f32 v[14:15], v[72:73], v[100:101] op_sel_hi:[0,1]
	v_pk_fma_f32 v[44:45], v[44:45], v[68:69], v[14:15] op_sel_hi:[1,0,1] neg_lo:[0,0,1] neg_hi:[0,0,1]
	v_pk_mul_f32 v[14:15], v[72:73], v[106:107] op_sel_hi:[0,1]
	v_pk_fma_f32 v[38:39], v[18:19], v[68:69], v[14:15] op_sel_hi:[1,0,1] neg_lo:[0,0,1] neg_hi:[0,0,1]
	v_pk_mul_f32 v[14:15], v[72:73], v[104:105] op_sel_hi:[0,1]
	v_pk_fma_f32 v[40:41], v[16:17], v[68:69], v[14:15] op_sel_hi:[1,0,1] neg_lo:[0,0,1] neg_hi:[0,0,1]
	v_pk_mul_f32 v[16:17], v[72:73], v[108:109] op_sel_hi:[0,1]
	v_pk_fma_f32 v[42:43], v[20:21], v[68:69], v[16:17] op_sel_hi:[1,0,1] neg_lo:[0,0,1] neg_hi:[0,0,1]
	v_pk_mul_f32 v[16:17], v[72:73], v[114:115] op_sel_hi:[0,1]
	v_pk_mul_f32 v[20:21], v[72:73], v[116:117] op_sel_hi:[0,1]
	v_pk_fma_f32 v[16:17], v[26:27], v[68:69], v[16:17] op_sel_hi:[1,0,1] neg_lo:[0,0,1] neg_hi:[0,0,1]
	v_pk_fma_f32 v[26:27], v[28:29], v[68:69], v[20:21] op_sel_hi:[1,0,1] neg_lo:[0,0,1] neg_hi:[0,0,1]
	v_pk_mul_f32 v[20:21], v[72:73], v[122:123] op_sel_hi:[0,1]
	v_pk_mul_f32 v[14:15], v[72:73], v[110:111] op_sel_hi:[0,1]
	v_pk_fma_f32 v[20:21], v[2:3], v[68:69], v[20:21] op_sel_hi:[1,0,1] neg_lo:[0,0,1] neg_hi:[0,0,1]
	v_pk_mul_f32 v[2:3], v[72:73], v[120:121] op_sel_hi:[0,1]
	v_pk_mul_f32 v[84:85], v[72:73], v[84:85] op_sel_hi:[0,1]
	v_pk_fma_f32 v[130:131], v[48:49], v[68:69], v[140:141] op_sel_hi:[1,0,1] neg_lo:[0,0,1] neg_hi:[0,0,1]
	v_pk_fma_f32 v[14:15], v[22:23], v[68:69], v[14:15] op_sel_hi:[1,0,1] neg_lo:[0,0,1] neg_hi:[0,0,1]
	v_pk_mul_f32 v[18:19], v[72:73], v[112:113] op_sel_hi:[0,1]
	v_pk_fma_f32 v[22:23], v[0:1], v[68:69], v[2:3] op_sel_hi:[1,0,1] neg_lo:[0,0,1] neg_hi:[0,0,1]
	s_waitcnt lgkmcnt(2)
; DI unsigned pack2(float a, float b) { f32x2_t v = {a, b}; bf16x2_t r = __builtin_convertvector(v, bf16x2_t); return __builtin_bit_cast(unsigned, r); }
; DI float xor32(float v) { return __shfl_xor(v, 32); }
; DI void task_attnA(const P& p, int layer, int task, bf16_t* sm, int dm) {
;     ...
;     for (int dt = 0; dt < 4; ++dt)
; #pragma unroll
;       for (int i = 0; i < 16; ++i) {
;         const int d = dt * 32 + 8 * (i >> 2) + 4 * lh + (i & 3);
;         const float o = O[dt][i] * inv - lam * xbuf[(qs * 128 + d) * 32 + lr];
;         O[dt][i] = o;
;         ss += o * o;
;       }
;     ss += xor32(ss);
;     const float r = rsqrtf(ss * (1.f / 128.f) + 1e-6f) * (1.f - li);
;     const float* sub = p.diff_subln + layer * 128;
;     bf16_t* dst = (dm ? (bf16_t*)(p.ws + WS_END) : aq) + (size_t)(b * S_ + qp) * 512 + h * 128;
; #pragma unroll
;     for (int dt = 0; dt < 4; ++dt)
; #pragma unroll
;       for (int qd = 0; qd < 4; ++qd) {
;         const int d = dt * 32 + 8 * qd + 4 * lh;
;         const float4 g4 = *(const float4*)(sub + d);
;         *(uint2*)(dst + d) = make_uint2(pack2(O[dt][4 * qd] * r * g4.x, O[dt][4 * qd + 1] * r * g4.y),
	v_pk_mul_f32 v[0:1], v[72:73], v[132:133] op_sel_hi:[0,1]
	v_pk_mul_f32 v[2:3], v[72:73], v[126:127] op_sel_hi:[0,1]
	v_pk_mul_f32 v[86:87], v[72:73], v[86:87] op_sel_hi:[0,1]
	v_pk_fma_f32 v[52:53], v[60:61], v[68:69], v[84:85] op_sel_hi:[1,0,1] neg_lo:[0,0,1] neg_hi:[0,0,1]
	v_pk_mul_f32 v[84:85], v[130:131], v[130:131]
	v_pk_fma_f32 v[24:25], v[24:25], v[68:69], v[18:19] op_sel_hi:[1,0,1] neg_lo:[0,0,1] neg_hi:[0,0,1]
	v_pk_mul_f32 v[18:19], v[72:73], v[118:119] op_sel_hi:[0,1]
	v_pk_fma_f32 v[0:1], v[6:7], v[68:69], v[0:1] op_sel_hi:[1,0,1] neg_lo:[0,0,1] neg_hi:[0,0,1]
	v_pk_fma_f32 v[4:5], v[4:5], v[68:69], v[2:3] op_sel_hi:[1,0,1] neg_lo:[0,0,1] neg_hi:[0,0,1]
	s_waitcnt lgkmcnt(0)
	v_pk_mul_f32 v[2:3], v[72:73], v[138:139] op_sel_hi:[0,1]
	v_pk_mul_f32 v[6:7], v[72:73], v[134:135] op_sel_hi:[0,1]
	v_pk_fma_f32 v[48:49], v[62:63], v[68:69], v[86:87] op_sel_hi:[1,0,1] neg_lo:[0,0,1] neg_hi:[0,0,1]
	v_pk_mul_f32 v[82:83], v[128:129], v[128:129]
	v_pk_fma_f32 v[18:19], v[30:31], v[68:69], v[18:19] op_sel_hi:[1,0,1] neg_lo:[0,0,1] neg_hi:[0,0,1]
	v_pk_fma_f32 v[2:3], v[10:11], v[68:69], v[2:3] op_sel_hi:[1,0,1] neg_lo:[0,0,1] neg_hi:[0,0,1]
	v_pk_fma_f32 v[6:7], v[8:9], v[68:69], v[6:7] op_sel_hi:[1,0,1] neg_lo:[0,0,1] neg_hi:[0,0,1]
	v_add_f32_e32 v68, v84, v85
	v_add_f32_e32 v68, v68, v82
	v_pk_mul_f32 v[140:141], v[80:81], v[80:81]
	v_add_f32_e32 v68, v68, v83
	v_add_f32_e32 v68, v68, v140
	v_pk_mul_f32 v[86:87], v[78:79], v[78:79]
	v_add_f32_e32 v68, v68, v141
	v_add_f32_e32 v68, v68, v86
	v_pk_mul_f32 v[144:145], v[76:77], v[76:77]
	v_add_f32_e32 v68, v68, v87
	v_add_f32_e32 v68, v68, v144
	v_pk_mul_f32 v[142:143], v[74:75], v[74:75]
	v_add_f32_e32 v68, v68, v145
	v_add_f32_e32 v68, v68, v142
	v_pk_mul_f32 v[148:149], v[52:53], v[52:53]
	v_add_f32_e32 v68, v68, v143
	v_add_f32_e32 v68, v68, v148
	v_pk_mul_f32 v[146:147], v[48:49], v[48:49]
	v_add_f32_e32 v68, v68, v149
	v_add_f32_e32 v68, v68, v146
	v_pk_mul_f32 v[88:89], v[54:55], v[54:55]
	v_add_f32_e32 v68, v68, v147
	v_add_f32_e32 v68, v68, v88
	v_pk_mul_f32 v[90:91], v[50:51], v[50:51]
	v_add_f32_e32 v68, v68, v89
	v_add_f32_e32 v68, v68, v90
	v_pk_mul_f32 v[92:93], v[56:57], v[56:57]
	v_add_f32_e32 v68, v68, v91
	v_add_f32_e32 v68, v68, v92
	v_pk_mul_f32 v[94:95], v[32:33], v[32:33]
	v_add_f32_e32 v68, v68, v93
	v_add_f32_e32 v68, v68, v94
	v_pk_mul_f32 v[96:97], v[58:59], v[58:59]
	v_add_f32_e32 v68, v68, v95
	v_add_f32_e32 v68, v68, v96
	v_pk_mul_f32 v[98:99], v[34:35], v[34:35]
	v_add_f32_e32 v68, v68, v97
	v_add_f32_e32 v68, v68, v98
	v_pk_mul_f32 v[100:101], v[44:45], v[44:45]
	v_add_f32_e32 v68, v68, v99
	v_add_f32_e32 v68, v68, v100
	v_pk_mul_f32 v[46:47], v[36:37], v[36:37]
	v_add_f32_e32 v68, v68, v101
	v_add_f32_e32 v46, v68, v46
	v_pk_mul_f32 v[104:105], v[40:41], v[40:41]
	v_add_f32_e32 v46, v46, v47
	v_add_f32_e32 v46, v46, v104
	v_pk_mul_f32 v[102:103], v[38:39], v[38:39]
	v_add_f32_e32 v46, v46, v105
	v_add_f32_e32 v46, v46, v102
	v_pk_mul_f32 v[108:109], v[42:43], v[42:43]
	v_add_f32_e32 v46, v46, v103
	v_add_f32_e32 v46, v46, v108
	v_pk_mul_f32 v[106:107], v[14:15], v[14:15]
	v_add_f32_e32 v46, v46, v109
	v_add_f32_e32 v46, v46, v106
	v_pk_mul_f32 v[112:113], v[24:25], v[24:25]
	v_add_f32_e32 v46, v46, v107
	v_add_f32_e32 v46, v46, v112
	v_pk_mul_f32 v[110:111], v[16:17], v[16:17]
	v_add_f32_e32 v46, v46, v113
	v_add_f32_e32 v46, v46, v110
	v_pk_mul_f32 v[28:29], v[26:27], v[26:27]
	v_add_f32_e32 v46, v46, v111
	v_add_f32_e32 v28, v46, v28
	v_pk_mul_f32 v[30:31], v[18:19], v[18:19]
	v_add_f32_e32 v28, v28, v29
	v_add_f32_e32 v28, v28, v30
	v_pk_mul_f32 v[116:117], v[22:23], v[22:23]
	v_add_f32_e32 v28, v28, v31
	v_add_f32_e32 v28, v28, v116
	v_pk_mul_f32 v[114:115], v[20:21], v[20:21]
	v_add_f32_e32 v28, v28, v117
	v_add_f32_e32 v28, v28, v114
	v_pk_mul_f32 v[120:121], v[4:5], v[4:5]
	v_add_f32_e32 v28, v28, v115
	v_add_f32_e32 v28, v28, v120
	v_pk_mul_f32 v[118:119], v[0:1], v[0:1]
	v_add_f32_e32 v28, v28, v121
	v_add_f32_e32 v28, v28, v118
	v_pk_mul_f32 v[8:9], v[6:7], v[6:7]
	v_add_f32_e32 v28, v28, v119
	v_add_f32_e32 v8, v28, v8
	v_pk_mul_f32 v[10:11], v[2:3], v[2:3]
	v_add_f32_e32 v8, v8, v9
	v_add_f32_e32 v8, v8, v10
	v_pk_mul_f32 v[60:61], v[70:71], v[70:71]
	v_add_f32_e32 v8, v8, v11
	v_add_f32_e32 v8, v8, v60
	v_pk_mul_f32 v[62:63], v[12:13], v[12:13]
	v_add_f32_e32 v8, v8, v61
	v_add_f32_e32 v8, v8, v62
	v_add_f32_e32 v8, v8, v63
	ds_bpermute_b32 v9, v69, v8
	s_waitcnt lgkmcnt(0)
	v_add_f32_e32 v8, v8, v9
	v_fmamk_f32 v8, v8, 0x3c000000, v194
	v_mul_f32_e32 v9, 0x4b800000, v8
	v_cmp_gt_f32_e32 vcc, s23, v8
	s_nop 1
	v_cndmask_b32_e32 v8, v8, v9, vcc
	v_rsq_f32_e32 v10, v8
	v_lshlrev_b32_e32 v8, 3, v137
	v_mov_b32_e32 v9, v193
	v_lshl_add_u64 v[28:29], v[124:125], 0, v[8:9]
	v_mul_f32_e32 v8, 0x45800000, v10
	v_cndmask_b32_e32 v8, v10, v8, vcc
	v_mul_f32_e32 v30, v136, v8
	v_pk_mul_f32 v[8:9], v[130:131], v[30:31] op_sel_hi:[1,0]
	v_pk_mul_f32 v[10:11], v[128:129], v[30:31] op_sel_hi:[1,0]
	s_waitcnt vmcnt(0)
; DI unsigned pack2(float a, float b) { f32x2_t v = {a, b}; bf16x2_t r = __builtin_convertvector(v, bf16x2_t); return __builtin_bit_cast(unsigned, r); }
; DI void task_attnA(const P& p, int layer, int task, bf16_t* sm, int dm) {
;     ...
; #pragma unroll
;     for (int dt = 0; dt < 4; ++dt)
; #pragma unroll
;       for (int qd = 0; qd < 4; ++qd) {
;         const int d = dt * 32 + 8 * qd + 4 * lh;
;         const float4 g4 = *(const float4*)(sub + d);
;         *(uint2*)(dst + d) = make_uint2(pack2(O[dt][4 * qd] * r * g4.x, O[dt][4 * qd + 1] * r * g4.y),
;                                         pack2(O[dt][4 * qd + 2] * r * g4.z, O[dt][4 * qd + 3] * r * g4.w));
;       }
	v_pk_mul_f32 v[8:9], v[64:65], v[8:9]
	v_pk_mul_f32 v[10:11], v[66:67], v[10:11]
	v_cvt_pk_bf16_f32 v8, v8, v9
	v_cvt_pk_bf16_f32 v9, v10, v11
	global_store_dwordx2 v[28:29], v[8:9], off
	global_load_dwordx4 v[8:11], v192, s[26:27] offset:32
	global_load_dwordx4 v[152:155], v192, s[26:27] offset:64
	global_load_dwordx4 v[156:159], v192, s[26:27] offset:96
	global_load_dwordx4 v[160:163], v192, s[26:27] offset:128
	global_load_dwordx4 v[164:167], v192, s[26:27] offset:160
	global_load_dwordx4 v[168:171], v192, s[26:27] offset:192
	global_load_dwordx4 v[172:175], v192, s[26:27] offset:224
	global_load_dwordx4 v[176:179], v192, s[26:27] offset:256
	global_load_dwordx4 v[180:183], v192, s[26:27] offset:288
	global_load_dwordx4 v[184:187], v192, s[26:27] offset:320
	global_load_dwordx4 v[188:191], v192, s[26:27] offset:352
	global_load_dwordx4 v[196:199], v192, s[26:27] offset:384
	global_load_dwordx4 v[200:203], v192, s[26:27] offset:416
	global_load_dwordx4 v[204:207], v192, s[26:27] offset:448
	global_load_dwordx4 v[208:211], v192, s[26:27] offset:480
	v_pk_mul_f32 v[46:47], v[80:81], v[30:31] op_sel_hi:[1,0]
	v_pk_mul_f32 v[60:61], v[78:79], v[30:31] op_sel_hi:[1,0]
	v_pk_mul_f32 v[48:49], v[48:49], v[30:31] op_sel_hi:[1,0]
	v_pk_mul_f32 v[32:33], v[32:33], v[30:31] op_sel_hi:[1,0]
	v_pk_mul_f32 v[34:35], v[34:35], v[30:31] op_sel_hi:[1,0]
	v_pk_mul_f32 v[14:15], v[14:15], v[30:31] op_sel_hi:[1,0]
	v_pk_mul_f32 v[16:17], v[16:17], v[30:31] op_sel_hi:[1,0]
	v_pk_mul_f32 v[4:5], v[4:5], v[30:31] op_sel_hi:[1,0]
	v_pk_mul_f32 v[0:1], v[0:1], v[30:31] op_sel_hi:[1,0]
	v_pk_mul_f32 v[2:3], v[2:3], v[30:31] op_sel_hi:[1,0]
	s_nop 0
	s_waitcnt vmcnt(14)
	v_pk_mul_f32 v[8:9], v[8:9], v[46:47]
	v_pk_mul_f32 v[10:11], v[10:11], v[60:61]
	v_cvt_pk_bf16_f32 v8, v8, v9
	v_cvt_pk_bf16_f32 v9, v10, v11
	global_store_dwordx2 v[28:29], v[8:9], off offset:16
	s_nop 0
	v_pk_mul_f32 v[46:47], v[76:77], v[30:31] op_sel_hi:[1,0]
	v_pk_mul_f32 v[60:61], v[74:75], v[30:31] op_sel_hi:[1,0]
	s_nop 0
	s_waitcnt vmcnt(14)
	v_pk_mul_f32 v[8:9], v[46:47], v[152:153]
	v_pk_mul_f32 v[10:11], v[60:61], v[154:155]
	v_cvt_pk_bf16_f32 v8, v8, v9
	v_cvt_pk_bf16_f32 v9, v10, v11
	global_store_dwordx2 v[28:29], v[8:9], off offset:32
	s_nop 0
	v_pk_mul_f32 v[46:47], v[52:53], v[30:31] op_sel_hi:[1,0]
	s_nop 0
	s_waitcnt vmcnt(14)
	v_pk_mul_f32 v[10:11], v[48:49], v[158:159]
	v_pk_mul_f32 v[8:9], v[46:47], v[156:157]
	v_pk_mul_f32 v[46:47], v[54:55], v[30:31] op_sel_hi:[1,0]
	v_cvt_pk_bf16_f32 v8, v8, v9
	v_cvt_pk_bf16_f32 v9, v10, v11
	global_store_dwordx2 v[28:29], v[8:9], off offset:48
	s_nop 0
	v_pk_mul_f32 v[48:49], v[50:51], v[30:31] op_sel_hi:[1,0]
	s_nop 0
	s_waitcnt vmcnt(14)
	v_pk_mul_f32 v[8:9], v[46:47], v[160:161]
	v_pk_mul_f32 v[10:11], v[48:49], v[162:163]
	v_cvt_pk_bf16_f32 v8, v8, v9
	v_cvt_pk_bf16_f32 v9, v10, v11
	global_store_dwordx2 v[28:29], v[8:9], off offset:64
	s_nop 0
	v_pk_mul_f32 v[46:47], v[56:57], v[30:31] op_sel_hi:[1,0]
	s_nop 0
	s_waitcnt vmcnt(14)
	v_pk_mul_f32 v[10:11], v[32:33], v[166:167]
	v_pk_mul_f32 v[8:9], v[46:47], v[164:165]
	v_pk_mul_f32 v[32:33], v[58:59], v[30:31] op_sel_hi:[1,0]
	v_cvt_pk_bf16_f32 v8, v8, v9
	v_cvt_pk_bf16_f32 v9, v10, v11
	global_store_dwordx2 v[28:29], v[8:9], off offset:80
	s_nop 0
	s_nop 0
	s_waitcnt vmcnt(14)
	v_pk_mul_f32 v[8:9], v[32:33], v[168:169]
	v_pk_mul_f32 v[10:11], v[34:35], v[170:171]
	v_cvt_pk_bf16_f32 v8, v8, v9
	v_cvt_pk_bf16_f32 v9, v10, v11
	global_store_dwordx2 v[28:29], v[8:9], off offset:96
	s_nop 0
	v_pk_mul_f32 v[32:33], v[44:45], v[30:31] op_sel_hi:[1,0]
	v_pk_mul_f32 v[34:35], v[36:37], v[30:31] op_sel_hi:[1,0]
	s_nop 0
	s_waitcnt vmcnt(14)
	v_pk_mul_f32 v[8:9], v[32:33], v[172:173]
	v_pk_mul_f32 v[10:11], v[34:35], v[174:175]
	v_cvt_pk_bf16_f32 v8, v8, v9
	v_cvt_pk_bf16_f32 v9, v10, v11
	global_store_dwordx2 v[28:29], v[8:9], off offset:112
	s_nop 0
	v_pk_mul_f32 v[32:33], v[40:41], v[30:31] op_sel_hi:[1,0]
	v_pk_mul_f32 v[34:35], v[38:39], v[30:31] op_sel_hi:[1,0]
	s_nop 0
	s_waitcnt vmcnt(14)
	v_pk_mul_f32 v[8:9], v[32:33], v[176:177]
	v_pk_mul_f32 v[10:11], v[34:35], v[178:179]
	v_cvt_pk_bf16_f32 v8, v8, v9
	v_cvt_pk_bf16_f32 v9, v10, v11
	global_store_dwordx2 v[28:29], v[8:9], off offset:128
	s_nop 0
	v_pk_mul_f32 v[32:33], v[42:43], v[30:31] op_sel_hi:[1,0]
	s_nop 0
	s_waitcnt vmcnt(14)
	v_pk_mul_f32 v[10:11], v[14:15], v[182:183]
	v_pk_mul_f32 v[8:9], v[32:33], v[180:181]
	v_pk_mul_f32 v[14:15], v[24:25], v[30:31] op_sel_hi:[1,0]
	v_cvt_pk_bf16_f32 v8, v8, v9
	v_cvt_pk_bf16_f32 v9, v10, v11
	global_store_dwordx2 v[28:29], v[8:9], off offset:144
	s_nop 0
	s_nop 0
	s_waitcnt vmcnt(14)
	v_pk_mul_f32 v[8:9], v[14:15], v[184:185]
	v_pk_mul_f32 v[10:11], v[16:17], v[186:187]
	v_cvt_pk_bf16_f32 v8, v8, v9
	v_cvt_pk_bf16_f32 v9, v10, v11
	global_store_dwordx2 v[28:29], v[8:9], off offset:160
	s_nop 0
	v_pk_mul_f32 v[14:15], v[26:27], v[30:31] op_sel_hi:[1,0]
	v_pk_mul_f32 v[16:17], v[18:19], v[30:31] op_sel_hi:[1,0]
	s_nop 0
	s_waitcnt vmcnt(14)
	v_pk_mul_f32 v[8:9], v[14:15], v[188:189]
	v_pk_mul_f32 v[10:11], v[16:17], v[190:191]
	v_cvt_pk_bf16_f32 v8, v8, v9
	v_cvt_pk_bf16_f32 v9, v10, v11
	global_store_dwordx2 v[28:29], v[8:9], off offset:176
	s_nop 0
	v_pk_mul_f32 v[14:15], v[22:23], v[30:31] op_sel_hi:[1,0]
	v_pk_mul_f32 v[16:17], v[20:21], v[30:31] op_sel_hi:[1,0]
	s_nop 0
	s_waitcnt vmcnt(14)
	v_pk_mul_f32 v[8:9], v[14:15], v[196:197]
	v_pk_mul_f32 v[10:11], v[16:17], v[198:199]
	v_cvt_pk_bf16_f32 v8, v8, v9
	v_cvt_pk_bf16_f32 v9, v10, v11
	global_store_dwordx2 v[28:29], v[8:9], off offset:192
	s_nop 0
	s_nop 0
	s_waitcnt vmcnt(14)
	v_pk_mul_f32 v[4:5], v[4:5], v[200:201]
	v_pk_mul_f32 v[0:1], v[0:1], v[202:203]
	v_cvt_pk_bf16_f32 v4, v4, v5
	v_cvt_pk_bf16_f32 v5, v0, v1
	global_store_dwordx2 v[28:29], v[4:5], off offset:208
	s_nop 0
	v_pk_mul_f32 v[0:1], v[6:7], v[30:31] op_sel_hi:[1,0]
	v_pk_mul_f32 v[4:5], v[70:71], v[30:31] op_sel_hi:[1,0]
	v_pk_mul_f32 v[6:7], v[12:13], v[30:31] op_sel_hi:[1,0]
	s_nop 0
	s_waitcnt vmcnt(14)
	v_pk_mul_f32 v[0:1], v[0:1], v[204:205]
	v_pk_mul_f32 v[2:3], v[2:3], v[206:207]
	v_cvt_pk_bf16_f32 v0, v0, v1
	v_cvt_pk_bf16_f32 v1, v2, v3
	global_store_dwordx2 v[28:29], v[0:1], off offset:224
	s_nop 0
	s_nop 0
	s_waitcnt vmcnt(14)
	v_pk_mul_f32 v[0:1], v[4:5], v[208:209]
	v_pk_mul_f32 v[2:3], v[6:7], v[210:211]
	v_cvt_pk_bf16_f32 v0, v0, v1
	v_cvt_pk_bf16_f32 v1, v2, v3
	global_store_dwordx2 v[28:29], v[0:1], off offset:240
